# GEMM K loops: the redundant second lgkmcnt(0) after each pre-MFMA barrier removed (12 sites)
# baseline (speedup 1.0000x reference)
.LBB0_628:
	s_add_u32 s36, s30, 0xfffc0080
	s_addc_u32 s37, s31, -1
	s_add_i32 s53, 0, 0x10000
	s_cmp_eq_u32 s52, 12
	s_cselect_b32 s39, s15, s37
	s_cselect_b32 s38, s48, s36
	v_add_u32_e32 v145, s53, v141
	s_cselect_b32 s37, s13, s51
	s_cselect_b32 s36, s49, s50
	s_add_i32 s56, 0, 0x14000
	ds_read_b128 v[146:149], v145
	ds_read_b128 v[150:153], v145 offset:1024
	ds_read_b128 v[164:167], v145 offset:2048
	ds_read_b128 v[168:171], v145 offset:3072
	v_add_u32_e32 v145, s56, v141
	ds_read_b128 v[176:179], v145
	ds_read_b128 v[180:183], v145 offset:1024
	ds_read_b128 v[184:187], v145 offset:2048
	ds_read_b128 v[212:215], v145 offset:3072
	v_lshl_add_u64 v[154:155], s[30:31], 0, v[136:137]
	s_add_i32 m0, s41, 0xc000
	ds_read_b128 v[216:219], v144
	ds_read_b128 v[220:223], v144 offset:1024
	ds_read_b128 v[224:227], v144 offset:2048
	ds_read_b128 v[228:231], v144 offset:3072
	ds_read_b128 v[232:235], v144 offset:4096
	ds_read_b128 v[236:239], v144 offset:5120
	ds_read_b128 v[240:243], v144 offset:6144
	ds_read_b128 v[244:247], v144 offset:7168
	global_load_lds_dwordx4 v[154:155], off
	v_lshl_add_u64 v[154:155], s[30:31], 0, v[138:139]
	s_add_i32 m0, s41, 0xe000
	s_nop 0
	global_load_lds_dwordx4 v[154:155], off
	s_waitcnt vmcnt(8)
	s_waitcnt lgkmcnt(0)
	s_barrier
	s_setprio 1
	v_mfma_f32_16x16x32_bf16 v[126:129], v[146:149], v[216:219], v[126:129]
	v_mfma_f32_16x16x32_bf16 v[122:125], v[164:167], v[216:219], v[122:125]
	v_mfma_f32_16x16x32_bf16 v[118:121], v[146:149], v[224:227], v[118:121]
	v_mfma_f32_16x16x32_bf16 v[110:113], v[164:167], v[224:227], v[110:113]
	v_mfma_f32_16x16x32_bf16 v[98:101], v[146:149], v[232:235], v[98:101]
	v_mfma_f32_16x16x32_bf16 v[90:93], v[164:167], v[232:235], v[90:93]
	v_mfma_f32_16x16x32_bf16 v[86:89], v[146:149], v[240:243], v[86:89]
	v_mfma_f32_16x16x32_bf16 v[78:81], v[164:167], v[240:243], v[78:81]
	v_mfma_f32_16x16x32_bf16 v[126:129], v[150:153], v[220:223], v[126:129]
	v_mfma_f32_16x16x32_bf16 v[122:125], v[168:171], v[220:223], v[122:125]
	v_mfma_f32_16x16x32_bf16 v[118:121], v[150:153], v[228:231], v[118:121]
	v_mfma_f32_16x16x32_bf16 v[110:113], v[168:171], v[228:231], v[110:113]
	v_mfma_f32_16x16x32_bf16 v[98:101], v[150:153], v[236:239], v[98:101]
	v_mfma_f32_16x16x32_bf16 v[90:93], v[168:171], v[236:239], v[90:93]
	v_mfma_f32_16x16x32_bf16 v[86:89], v[150:153], v[244:247], v[86:89]
	v_mfma_f32_16x16x32_bf16 v[78:81], v[168:171], v[244:247], v[78:81]
	s_setprio 0
	s_setprio 1
	v_mfma_f32_16x16x32_bf16 v[114:117], v[176:179], v[216:219], v[114:117]
	v_mfma_f32_16x16x32_bf16 v[106:109], v[184:187], v[216:219], v[106:109]
	v_mfma_f32_16x16x32_bf16 v[102:105], v[176:179], v[224:227], v[102:105]
	v_mfma_f32_16x16x32_bf16 v[94:97], v[184:187], v[224:227], v[94:97]
	v_mfma_f32_16x16x32_bf16 v[82:85], v[176:179], v[232:235], v[82:85]
	v_mfma_f32_16x16x32_bf16 v[74:77], v[184:187], v[232:235], v[74:77]
	v_mfma_f32_16x16x32_bf16 v[70:73], v[176:179], v[240:243], v[70:73]
	v_mfma_f32_16x16x32_bf16 v[66:69], v[184:187], v[240:243], v[66:69]
	v_mfma_f32_16x16x32_bf16 v[114:117], v[180:183], v[220:223], v[114:117]
	v_mfma_f32_16x16x32_bf16 v[106:109], v[212:215], v[220:223], v[106:109]
	v_mfma_f32_16x16x32_bf16 v[102:105], v[180:183], v[228:231], v[102:105]
	v_mfma_f32_16x16x32_bf16 v[94:97], v[212:215], v[228:231], v[94:97]
	v_mfma_f32_16x16x32_bf16 v[82:85], v[180:183], v[236:239], v[82:85]
	v_mfma_f32_16x16x32_bf16 v[74:77], v[212:215], v[236:239], v[74:77]
	v_mfma_f32_16x16x32_bf16 v[70:73], v[180:183], v[244:247], v[70:73]
	v_mfma_f32_16x16x32_bf16 v[66:69], v[212:215], v[244:247], v[66:69]
	s_setprio 0
	s_barrier
	s_add_i32 s53, s53, s40
	v_lshl_add_u64 v[154:155], s[36:37], 0, v[0:1]
	s_mov_b32 m0, s53
	ds_read_b128 v[216:219], v144 offset:16384
	ds_read_b128 v[220:223], v144 offset:17408
	ds_read_b128 v[224:227], v144 offset:18432
	ds_read_b128 v[228:231], v144 offset:19456
	ds_read_b128 v[232:235], v144 offset:20480
	ds_read_b128 v[236:239], v144 offset:21504
	ds_read_b128 v[240:243], v144 offset:22528
	ds_read_b128 v[244:247], v144 offset:23552
	global_load_lds_dwordx4 v[154:155], off
	s_add_i32 m0, s53, 0x2000
	s_add_u32 s54, s36, 0x40000
	v_lshl_add_u64 v[172:173], s[36:37], 0, v[134:135]
	s_addc_u32 s55, s37, 0
	s_add_i32 s53, s56, s40
	global_load_lds_dwordx4 v[172:173], off
	v_lshl_add_u64 v[198:199], s[54:55], 0, v[0:1]
	s_mov_b32 m0, s53
	v_lshl_add_u64 v[248:249], s[38:39], 0, v[132:133]
	global_load_lds_dwordx4 v[198:199], off
	v_lshl_add_u64 v[198:199], s[54:55], 0, v[134:135]
	s_add_i32 m0, s53, 0x2000
	s_nop 0
	global_load_lds_dwordx4 v[198:199], off
	v_lshl_add_u64 v[198:199], s[38:39], 0, v[130:131]
	s_mov_b32 m0, s41
	s_nop 0
	global_load_lds_dwordx4 v[198:199], off
	s_mov_b32 m0, s42
	s_nop 0
	global_load_lds_dwordx4 v[248:249], off
	s_waitcnt vmcnt(8)
	s_waitcnt lgkmcnt(0)
	s_barrier
	s_setprio 1
	v_mfma_f32_16x16x32_bf16 v[62:65], v[146:149], v[216:219], v[62:65]
	v_mfma_f32_16x16x32_bf16 v[58:61], v[164:167], v[216:219], v[58:61]
	v_mfma_f32_16x16x32_bf16 v[54:57], v[146:149], v[224:227], v[54:57]
	v_mfma_f32_16x16x32_bf16 v[46:49], v[164:167], v[224:227], v[46:49]
	v_mfma_f32_16x16x32_bf16 v[34:37], v[146:149], v[232:235], v[34:37]
	v_mfma_f32_16x16x32_bf16 v[26:29], v[164:167], v[232:235], v[26:29]
	v_mfma_f32_16x16x32_bf16 v[22:25], v[146:149], v[240:243], v[22:25]
	v_mfma_f32_16x16x32_bf16 v[14:17], v[164:167], v[240:243], v[14:17]
	v_mfma_f32_16x16x32_bf16 v[62:65], v[150:153], v[220:223], v[62:65]
	v_mfma_f32_16x16x32_bf16 v[58:61], v[168:171], v[220:223], v[58:61]
	v_mfma_f32_16x16x32_bf16 v[54:57], v[150:153], v[228:231], v[54:57]
	v_mfma_f32_16x16x32_bf16 v[46:49], v[168:171], v[228:231], v[46:49]
	v_mfma_f32_16x16x32_bf16 v[34:37], v[150:153], v[236:239], v[34:37]
	v_mfma_f32_16x16x32_bf16 v[26:29], v[168:171], v[236:239], v[26:29]
	v_mfma_f32_16x16x32_bf16 v[22:25], v[150:153], v[244:247], v[22:25]
	v_mfma_f32_16x16x32_bf16 v[14:17], v[168:171], v[244:247], v[14:17]
	s_setprio 0
	s_setprio 1
	v_mfma_f32_16x16x32_bf16 v[50:53], v[176:179], v[216:219], v[50:53]
	v_mfma_f32_16x16x32_bf16 v[42:45], v[184:187], v[216:219], v[42:45]
	v_mfma_f32_16x16x32_bf16 v[38:41], v[176:179], v[224:227], v[38:41]
	v_mfma_f32_16x16x32_bf16 v[30:33], v[184:187], v[224:227], v[30:33]
	v_mfma_f32_16x16x32_bf16 v[18:21], v[176:179], v[232:235], v[18:21]
	v_mfma_f32_16x16x32_bf16 v[10:13], v[184:187], v[232:235], v[10:13]
	v_mfma_f32_16x16x32_bf16 v[6:9], v[176:179], v[240:243], v[6:9]
	v_mfma_f32_16x16x32_bf16 v[2:5], v[184:187], v[240:243], v[2:5]
	v_mfma_f32_16x16x32_bf16 v[50:53], v[180:183], v[220:223], v[50:53]
	v_mfma_f32_16x16x32_bf16 v[42:45], v[212:215], v[220:223], v[42:45]
	v_mfma_f32_16x16x32_bf16 v[38:41], v[180:183], v[228:231], v[38:41]
	v_mfma_f32_16x16x32_bf16 v[30:33], v[212:215], v[228:231], v[30:33]
	v_mfma_f32_16x16x32_bf16 v[18:21], v[180:183], v[236:239], v[18:21]
	v_mfma_f32_16x16x32_bf16 v[10:13], v[212:215], v[236:239], v[10:13]
	v_mfma_f32_16x16x32_bf16 v[6:9], v[180:183], v[244:247], v[6:9]
	v_mfma_f32_16x16x32_bf16 v[2:5], v[212:215], v[244:247], v[2:5]
	s_setprio 0
	s_barrier
	s_add_i32 s53, 0, 0x18000
	v_add_u32_e32 v145, s53, v141
	s_add_i32 s54, 0, 0x1c000
	ds_read_b128 v[146:149], v145
	ds_read_b128 v[150:153], v145 offset:1024
	ds_read_b128 v[164:167], v145 offset:2048
	ds_read_b128 v[168:171], v145 offset:3072
	v_add_u32_e32 v145, s54, v141
	ds_read_b128 v[176:179], v145
	ds_read_b128 v[180:183], v145 offset:1024
	ds_read_b128 v[184:187], v145 offset:2048
	ds_read_b128 v[212:215], v145 offset:3072
	s_add_u32 s38, s38, 0x40000
	s_addc_u32 s39, s39, 0
	s_mov_b32 m0, s43
	v_lshl_add_u64 v[250:251], s[38:39], 0, v[130:131]
	ds_read_b128 v[216:219], v144 offset:32768
	ds_read_b128 v[220:223], v144 offset:33792
	ds_read_b128 v[224:227], v144 offset:34816
	ds_read_b128 v[228:231], v144 offset:35840
	ds_read_b128 v[232:235], v144 offset:36864
	ds_read_b128 v[236:239], v144 offset:37888
	ds_read_b128 v[240:243], v144 offset:38912
	ds_read_b128 v[244:247], v144 offset:39936
	global_load_lds_dwordx4 v[250:251], off
	v_lshl_add_u64 v[250:251], s[38:39], 0, v[132:133]
	s_mov_b32 m0, s44
	s_nop 0
	global_load_lds_dwordx4 v[250:251], off
	s_waitcnt vmcnt(8)
	s_waitcnt lgkmcnt(0)
	s_barrier
	s_setprio 1
	v_mfma_f32_16x16x32_bf16 v[126:129], v[146:149], v[216:219], v[126:129]
	v_mfma_f32_16x16x32_bf16 v[122:125], v[164:167], v[216:219], v[122:125]
	v_mfma_f32_16x16x32_bf16 v[118:121], v[146:149], v[224:227], v[118:121]
	v_mfma_f32_16x16x32_bf16 v[110:113], v[164:167], v[224:227], v[110:113]
	v_mfma_f32_16x16x32_bf16 v[98:101], v[146:149], v[232:235], v[98:101]
	v_mfma_f32_16x16x32_bf16 v[90:93], v[164:167], v[232:235], v[90:93]
	v_mfma_f32_16x16x32_bf16 v[86:89], v[146:149], v[240:243], v[86:89]
	v_mfma_f32_16x16x32_bf16 v[78:81], v[164:167], v[240:243], v[78:81]
	v_mfma_f32_16x16x32_bf16 v[126:129], v[150:153], v[220:223], v[126:129]
	v_mfma_f32_16x16x32_bf16 v[122:125], v[168:171], v[220:223], v[122:125]
	v_mfma_f32_16x16x32_bf16 v[118:121], v[150:153], v[228:231], v[118:121]
	v_mfma_f32_16x16x32_bf16 v[110:113], v[168:171], v[228:231], v[110:113]
	v_mfma_f32_16x16x32_bf16 v[98:101], v[150:153], v[236:239], v[98:101]
	v_mfma_f32_16x16x32_bf16 v[90:93], v[168:171], v[236:239], v[90:93]
	v_mfma_f32_16x16x32_bf16 v[86:89], v[150:153], v[244:247], v[86:89]
	v_mfma_f32_16x16x32_bf16 v[78:81], v[168:171], v[244:247], v[78:81]
	s_setprio 0
	s_setprio 1
	v_mfma_f32_16x16x32_bf16 v[114:117], v[176:179], v[216:219], v[114:117]
	v_mfma_f32_16x16x32_bf16 v[106:109], v[184:187], v[216:219], v[106:109]
	v_mfma_f32_16x16x32_bf16 v[102:105], v[176:179], v[224:227], v[102:105]
	v_mfma_f32_16x16x32_bf16 v[94:97], v[184:187], v[224:227], v[94:97]
	v_mfma_f32_16x16x32_bf16 v[82:85], v[176:179], v[232:235], v[82:85]
	v_mfma_f32_16x16x32_bf16 v[74:77], v[184:187], v[232:235], v[74:77]
	v_mfma_f32_16x16x32_bf16 v[70:73], v[176:179], v[240:243], v[70:73]
	v_mfma_f32_16x16x32_bf16 v[66:69], v[184:187], v[240:243], v[66:69]
	v_mfma_f32_16x16x32_bf16 v[114:117], v[180:183], v[220:223], v[114:117]
	v_mfma_f32_16x16x32_bf16 v[106:109], v[212:215], v[220:223], v[106:109]
	v_mfma_f32_16x16x32_bf16 v[102:105], v[180:183], v[228:231], v[102:105]
	v_mfma_f32_16x16x32_bf16 v[94:97], v[212:215], v[228:231], v[94:97]
	v_mfma_f32_16x16x32_bf16 v[82:85], v[180:183], v[236:239], v[82:85]
	v_mfma_f32_16x16x32_bf16 v[74:77], v[212:215], v[236:239], v[74:77]
	v_mfma_f32_16x16x32_bf16 v[70:73], v[180:183], v[244:247], v[70:73]
	v_mfma_f32_16x16x32_bf16 v[66:69], v[212:215], v[244:247], v[66:69]
	s_setprio 0
	s_barrier
	s_add_i32 s38, s53, s40
	v_lshl_add_u64 v[154:155], v[154:155], 0, s[20:21]
	s_mov_b32 m0, s38
	ds_read_b128 v[216:219], v144 offset:49152
	ds_read_b128 v[220:223], v144 offset:50176
	ds_read_b128 v[224:227], v144 offset:51200
	ds_read_b128 v[228:231], v144 offset:52224
	ds_read_b128 v[232:235], v144 offset:53248
	ds_read_b128 v[236:239], v144 offset:54272
	ds_read_b128 v[240:243], v144 offset:55296
	ds_read_b128 v[244:247], v144 offset:56320
	global_load_lds_dwordx4 v[154:155], off
	s_add_i32 m0, s38, 0x2000
	s_add_u32 s36, s36, 0x40080
	v_lshl_add_u64 v[154:155], v[172:173], 0, s[20:21]
	s_addc_u32 s37, s37, 0
	s_add_i32 s38, s54, s40
	global_load_lds_dwordx4 v[154:155], off
	v_lshl_add_u64 v[154:155], s[36:37], 0, v[0:1]
	s_mov_b32 m0, s38
	s_nop 0
	global_load_lds_dwordx4 v[154:155], off
	v_lshl_add_u64 v[154:155], s[36:37], 0, v[134:135]
	s_add_i32 m0, s38, 0x2000
	s_nop 0
	global_load_lds_dwordx4 v[154:155], off
	v_lshl_add_u64 v[154:155], v[198:199], 0, s[20:21]
	s_mov_b32 m0, s45
	s_nop 0
	global_load_lds_dwordx4 v[154:155], off
	v_lshl_add_u64 v[154:155], v[248:249], 0, s[20:21]
	s_mov_b32 m0, s46
	s_nop 0
	global_load_lds_dwordx4 v[154:155], off
	s_waitcnt vmcnt(8)
	s_waitcnt lgkmcnt(0)
	s_barrier
	s_setprio 1
	v_mfma_f32_16x16x32_bf16 v[62:65], v[146:149], v[216:219], v[62:65]
	v_mfma_f32_16x16x32_bf16 v[58:61], v[164:167], v[216:219], v[58:61]
	v_mfma_f32_16x16x32_bf16 v[54:57], v[146:149], v[224:227], v[54:57]
	v_mfma_f32_16x16x32_bf16 v[46:49], v[164:167], v[224:227], v[46:49]
	v_mfma_f32_16x16x32_bf16 v[34:37], v[146:149], v[232:235], v[34:37]
	v_mfma_f32_16x16x32_bf16 v[26:29], v[164:167], v[232:235], v[26:29]
	v_mfma_f32_16x16x32_bf16 v[22:25], v[146:149], v[240:243], v[22:25]
	v_mfma_f32_16x16x32_bf16 v[14:17], v[164:167], v[240:243], v[14:17]
	v_mfma_f32_16x16x32_bf16 v[62:65], v[150:153], v[220:223], v[62:65]
	v_mfma_f32_16x16x32_bf16 v[58:61], v[168:171], v[220:223], v[58:61]
	v_mfma_f32_16x16x32_bf16 v[54:57], v[150:153], v[228:231], v[54:57]
	v_mfma_f32_16x16x32_bf16 v[46:49], v[168:171], v[228:231], v[46:49]
	v_mfma_f32_16x16x32_bf16 v[34:37], v[150:153], v[236:239], v[34:37]
	v_mfma_f32_16x16x32_bf16 v[26:29], v[168:171], v[236:239], v[26:29]
	v_mfma_f32_16x16x32_bf16 v[22:25], v[150:153], v[244:247], v[22:25]
	v_mfma_f32_16x16x32_bf16 v[14:17], v[168:171], v[244:247], v[14:17]
	s_setprio 0
	s_setprio 1
	v_mfma_f32_16x16x32_bf16 v[50:53], v[176:179], v[216:219], v[50:53]
	v_mfma_f32_16x16x32_bf16 v[42:45], v[184:187], v[216:219], v[42:45]
	v_mfma_f32_16x16x32_bf16 v[38:41], v[176:179], v[224:227], v[38:41]
	v_mfma_f32_16x16x32_bf16 v[30:33], v[184:187], v[224:227], v[30:33]
	v_mfma_f32_16x16x32_bf16 v[18:21], v[176:179], v[232:235], v[18:21]
	v_mfma_f32_16x16x32_bf16 v[10:13], v[184:187], v[232:235], v[10:13]
	v_mfma_f32_16x16x32_bf16 v[6:9], v[176:179], v[240:243], v[6:9]
	v_mfma_f32_16x16x32_bf16 v[2:5], v[184:187], v[240:243], v[2:5]
	v_mfma_f32_16x16x32_bf16 v[50:53], v[180:183], v[220:223], v[50:53]
	v_mfma_f32_16x16x32_bf16 v[42:45], v[212:215], v[220:223], v[42:45]
	v_mfma_f32_16x16x32_bf16 v[38:41], v[180:183], v[228:231], v[38:41]
	v_mfma_f32_16x16x32_bf16 v[30:33], v[212:215], v[228:231], v[30:33]
	v_mfma_f32_16x16x32_bf16 v[18:21], v[180:183], v[236:239], v[18:21]
	v_mfma_f32_16x16x32_bf16 v[10:13], v[212:215], v[236:239], v[10:13]
	v_mfma_f32_16x16x32_bf16 v[6:9], v[180:183], v[244:247], v[6:9]
	v_mfma_f32_16x16x32_bf16 v[2:5], v[212:215], v[244:247], v[2:5]
	s_setprio 0
	s_barrier
	s_add_i32 s52, s52, 2
	s_add_u32 s30, s30, 0x100
	s_addc_u32 s31, s31, 0
	s_add_u32 s50, s50, 0x100
	s_addc_u32 s51, s51, 0
	s_cmp_gt_u32 s52, 13
	s_cbranch_scc0 .LBB0_628
	s_and_b64 vcc, exec, s[8:9]
	s_cbranch_vccz .LBB0_631
	s_barrier

.LBB0_682:
	s_add_i32 s58, s38, 2
	s_add_u32 s59, s12, 0x80
	s_addc_u32 s39, s13, 0
	s_add_i32 s42, 0, 0x10000
	s_cmp_eq_u32 s95, s38
	s_cselect_b32 s39, s55, s39
	s_cselect_b32 s38, s54, s59
	s_cselect_b32 vcc_hi, s57, s41
	s_cselect_b32 vcc_lo, s56, s40
	s_add_i32 s43, 0, 0x14000
	v_add_u32_e32 v54, s42, v174
	v_add_u32_e32 v172, s43, v174
	ds_read_b128 v[38:41], v54
	ds_read_b128 v[46:49], v54 offset:1024
	ds_read_b128 v[50:53], v54 offset:2048
	ds_read_b128 v[54:57], v54 offset:3072
	ds_read_b128 v[164:167], v172
	ds_read_b128 v[168:171], v172 offset:1024
	ds_read_b128 v[178:181], v172 offset:2048
	ds_read_b128 v[182:185], v172 offset:3072
	v_lshl_add_u64 v[172:173], s[12:13], 0, v[152:153]
	s_add_i32 m0, s62, 0xc000
	ds_read_b128 v[212:215], v177
	ds_read_b128 v[216:219], v177 offset:1024
	ds_read_b128 v[220:223], v177 offset:2048
	ds_read_b128 v[224:227], v177 offset:3072
	ds_read_b128 v[228:231], v177 offset:4096
	ds_read_b128 v[232:235], v177 offset:5120
	ds_read_b128 v[236:239], v177 offset:6144
	ds_read_b128 v[240:243], v177 offset:7168
	global_load_lds_dwordx4 v[172:173], off
	v_lshl_add_u64 v[172:173], s[12:13], 0, v[154:155]
	s_add_i32 m0, s62, 0xe000
	s_nop 0
	global_load_lds_dwordx4 v[172:173], off
	s_waitcnt vmcnt(8)
	s_waitcnt lgkmcnt(0)
	s_barrier
	s_setprio 1
	v_mfma_f32_16x16x32_bf16 v[142:145], v[38:41], v[212:215], v[142:145]
	v_mfma_f32_16x16x32_bf16 v[138:141], v[50:53], v[212:215], v[138:141]
	v_mfma_f32_16x16x32_bf16 v[126:129], v[38:41], v[220:223], v[126:129]
	v_mfma_f32_16x16x32_bf16 v[122:125], v[50:53], v[220:223], v[122:125]
	v_mfma_f32_16x16x32_bf16 v[110:113], v[38:41], v[228:231], v[110:113]
	v_mfma_f32_16x16x32_bf16 v[106:109], v[50:53], v[228:231], v[106:109]
	v_mfma_f32_16x16x32_bf16 v[94:97], v[38:41], v[236:239], v[94:97]
	v_mfma_f32_16x16x32_bf16 v[90:93], v[50:53], v[236:239], v[90:93]
	v_mfma_f32_16x16x32_bf16 v[142:145], v[46:49], v[216:219], v[142:145]
	v_mfma_f32_16x16x32_bf16 v[138:141], v[54:57], v[216:219], v[138:141]
	v_mfma_f32_16x16x32_bf16 v[126:129], v[46:49], v[224:227], v[126:129]
	v_mfma_f32_16x16x32_bf16 v[122:125], v[54:57], v[224:227], v[122:125]
	v_mfma_f32_16x16x32_bf16 v[110:113], v[46:49], v[232:235], v[110:113]
	v_mfma_f32_16x16x32_bf16 v[106:109], v[54:57], v[232:235], v[106:109]
	v_mfma_f32_16x16x32_bf16 v[94:97], v[46:49], v[240:243], v[94:97]
	v_mfma_f32_16x16x32_bf16 v[90:93], v[54:57], v[240:243], v[90:93]
	s_setprio 0
	s_setprio 1
	v_mfma_f32_16x16x32_bf16 v[134:137], v[164:167], v[212:215], v[134:137]
	v_mfma_f32_16x16x32_bf16 v[130:133], v[178:181], v[212:215], v[130:133]
	v_mfma_f32_16x16x32_bf16 v[118:121], v[164:167], v[220:223], v[118:121]
	v_mfma_f32_16x16x32_bf16 v[114:117], v[178:181], v[220:223], v[114:117]
	v_mfma_f32_16x16x32_bf16 v[102:105], v[164:167], v[228:231], v[102:105]
	v_mfma_f32_16x16x32_bf16 v[98:101], v[178:181], v[228:231], v[98:101]
	v_mfma_f32_16x16x32_bf16 v[86:89], v[164:167], v[236:239], v[86:89]
	v_mfma_f32_16x16x32_bf16 v[82:85], v[178:181], v[236:239], v[82:85]
	v_mfma_f32_16x16x32_bf16 v[134:137], v[168:171], v[216:219], v[134:137]
	v_mfma_f32_16x16x32_bf16 v[130:133], v[182:185], v[216:219], v[130:133]
	v_mfma_f32_16x16x32_bf16 v[118:121], v[168:171], v[224:227], v[118:121]
	v_mfma_f32_16x16x32_bf16 v[114:117], v[182:185], v[224:227], v[114:117]
	v_mfma_f32_16x16x32_bf16 v[102:105], v[168:171], v[232:235], v[102:105]
	v_mfma_f32_16x16x32_bf16 v[98:101], v[182:185], v[232:235], v[98:101]
	v_mfma_f32_16x16x32_bf16 v[86:89], v[168:171], v[240:243], v[86:89]
	v_mfma_f32_16x16x32_bf16 v[82:85], v[182:185], v[240:243], v[82:85]
	s_setprio 0
	s_barrier
	s_add_i32 s42, s42, s61
	v_lshl_add_u64 v[172:173], vcc, 0, v[0:1]
	s_mov_b32 m0, s42
	ds_read_b128 v[212:215], v177 offset:16384
	ds_read_b128 v[216:219], v177 offset:17408
	ds_read_b128 v[220:223], v177 offset:18432
	ds_read_b128 v[224:227], v177 offset:19456
	ds_read_b128 v[228:231], v177 offset:20480
	ds_read_b128 v[232:235], v177 offset:21504
	ds_read_b128 v[236:239], v177 offset:22528
	ds_read_b128 v[240:243], v177 offset:23552
	global_load_lds_dwordx4 v[172:173], off
	s_add_i32 m0, s42, 0x2000
	v_lshl_add_u64 v[186:187], vcc, 0, v[150:151]
	s_add_u32 vcc_lo, vcc_lo, s7
	s_addc_u32 vcc_hi, vcc_hi, 0
	s_add_i32 s42, s43, s61
	global_load_lds_dwordx4 v[186:187], off
	v_lshl_add_u64 v[198:199], vcc, 0, v[0:1]
	s_mov_b32 m0, s42
	v_lshl_add_u64 v[244:245], vcc, 0, v[150:151]
	global_load_lds_dwordx4 v[198:199], off
	s_add_i32 m0, s42, 0x2000
	v_lshl_add_u64 v[246:247], s[38:39], 0, v[146:147]
	global_load_lds_dwordx4 v[244:245], off
	s_mov_b32 m0, s62
	v_lshl_add_u64 v[248:249], s[38:39], 0, v[148:149]
	global_load_lds_dwordx4 v[246:247], off
	s_mov_b32 m0, s63
	s_nop 0
	global_load_lds_dwordx4 v[248:249], off
	s_waitcnt vmcnt(8)
	s_waitcnt lgkmcnt(0)
	s_barrier
	s_setprio 1
	v_mfma_f32_16x16x32_bf16 v[78:81], v[38:41], v[212:215], v[78:81]
	v_mfma_f32_16x16x32_bf16 v[74:77], v[50:53], v[212:215], v[74:77]
	v_mfma_f32_16x16x32_bf16 v[62:65], v[38:41], v[220:223], v[62:65]
	v_mfma_f32_16x16x32_bf16 v[58:61], v[50:53], v[220:223], v[58:61]
	v_mfma_f32_16x16x32_bf16 v[30:33], v[38:41], v[228:231], v[30:33]
	v_mfma_f32_16x16x32_bf16 v[26:29], v[50:53], v[228:231], v[26:29]
	v_mfma_f32_16x16x32_bf16 v[14:17], v[38:41], v[236:239], v[14:17]
	v_mfma_f32_16x16x32_bf16 v[10:13], v[50:53], v[236:239], v[10:13]
	v_mfma_f32_16x16x32_bf16 v[78:81], v[46:49], v[216:219], v[78:81]
	v_mfma_f32_16x16x32_bf16 v[74:77], v[54:57], v[216:219], v[74:77]
	v_mfma_f32_16x16x32_bf16 v[62:65], v[46:49], v[224:227], v[62:65]
	v_mfma_f32_16x16x32_bf16 v[58:61], v[54:57], v[224:227], v[58:61]
	v_mfma_f32_16x16x32_bf16 v[30:33], v[46:49], v[232:235], v[30:33]
	v_mfma_f32_16x16x32_bf16 v[26:29], v[54:57], v[232:235], v[26:29]
	v_mfma_f32_16x16x32_bf16 v[14:17], v[46:49], v[240:243], v[14:17]
	v_mfma_f32_16x16x32_bf16 v[10:13], v[54:57], v[240:243], v[10:13]
	s_setprio 0
	s_setprio 1
	v_mfma_f32_16x16x32_bf16 v[42:45], v[164:167], v[220:223], v[42:45]
	v_mfma_f32_16x16x32_bf16 v[34:37], v[178:181], v[220:223], v[34:37]
	v_mfma_f32_16x16x32_bf16 v[22:25], v[164:167], v[228:231], v[22:25]
	v_mfma_f32_16x16x32_bf16 v[18:21], v[178:181], v[228:231], v[18:21]
	v_mfma_f32_16x16x32_bf16 v[6:9], v[164:167], v[236:239], v[6:9]
	v_mfma_f32_16x16x32_bf16 v[2:5], v[178:181], v[236:239], v[2:5]
	v_mfma_f32_16x16x32_bf16 v[38:41], v[164:167], v[212:215], v[70:73]
	v_mfma_f32_16x16x32_bf16 v[46:49], v[178:181], v[212:215], v[66:69]
	v_mfma_f32_16x16x32_bf16 v[42:45], v[168:171], v[224:227], v[42:45]
	v_mfma_f32_16x16x32_bf16 v[34:37], v[182:185], v[224:227], v[34:37]
	v_mfma_f32_16x16x32_bf16 v[22:25], v[168:171], v[232:235], v[22:25]
	v_mfma_f32_16x16x32_bf16 v[18:21], v[182:185], v[232:235], v[18:21]
	v_mfma_f32_16x16x32_bf16 v[6:9], v[168:171], v[240:243], v[6:9]
	v_mfma_f32_16x16x32_bf16 v[2:5], v[182:185], v[240:243], v[2:5]
	v_mfma_f32_16x16x32_bf16 v[38:41], v[168:171], v[216:219], v[38:41]
	v_mfma_f32_16x16x32_bf16 v[46:49], v[182:185], v[216:219], v[46:49]
	s_setprio 0
	s_barrier
	s_add_i32 s42, 0, 0x18000
	s_add_i32 s43, 0, 0x1c000
	v_add_u32_e32 v70, s42, v174
	v_add_u32_e32 v182, s43, v174
	ds_read_b128 v[50:53], v70
	ds_read_b128 v[54:57], v70 offset:1024
	ds_read_b128 v[66:69], v70 offset:2048
	ds_read_b128 v[70:73], v70 offset:3072
	ds_read_b128 v[164:167], v182
	ds_read_b128 v[168:171], v182 offset:1024
	ds_read_b128 v[178:181], v182 offset:2048
	ds_read_b128 v[182:185], v182 offset:3072
	s_add_u32 s38, s38, s26
	s_addc_u32 s39, s39, 0
	s_mov_b32 m0, s64
	v_lshl_add_u64 v[250:251], s[38:39], 0, v[146:147]
	ds_read_b128 v[212:215], v177 offset:32768
	ds_read_b128 v[216:219], v177 offset:33792
	ds_read_b128 v[220:223], v177 offset:34816
	ds_read_b128 v[224:227], v177 offset:35840
	ds_read_b128 v[228:231], v177 offset:36864
	ds_read_b128 v[232:235], v177 offset:37888
	ds_read_b128 v[236:239], v177 offset:38912
	ds_read_b128 v[240:243], v177 offset:39936
	global_load_lds_dwordx4 v[250:251], off
	v_lshl_add_u64 v[250:251], s[38:39], 0, v[148:149]
	s_mov_b32 m0, s65
	s_nop 0
	global_load_lds_dwordx4 v[250:251], off
	s_waitcnt vmcnt(8)
	s_waitcnt lgkmcnt(0)
	s_barrier
	s_setprio 1
	v_mfma_f32_16x16x32_bf16 v[142:145], v[50:53], v[212:215], v[142:145]
	v_mfma_f32_16x16x32_bf16 v[138:141], v[66:69], v[212:215], v[138:141]
	v_mfma_f32_16x16x32_bf16 v[126:129], v[50:53], v[220:223], v[126:129]
	v_mfma_f32_16x16x32_bf16 v[122:125], v[66:69], v[220:223], v[122:125]
	v_mfma_f32_16x16x32_bf16 v[110:113], v[50:53], v[228:231], v[110:113]
	v_mfma_f32_16x16x32_bf16 v[106:109], v[66:69], v[228:231], v[106:109]
	v_mfma_f32_16x16x32_bf16 v[94:97], v[50:53], v[236:239], v[94:97]
	v_mfma_f32_16x16x32_bf16 v[90:93], v[66:69], v[236:239], v[90:93]
	v_mfma_f32_16x16x32_bf16 v[142:145], v[54:57], v[216:219], v[142:145]
	v_mfma_f32_16x16x32_bf16 v[138:141], v[70:73], v[216:219], v[138:141]
	v_mfma_f32_16x16x32_bf16 v[126:129], v[54:57], v[224:227], v[126:129]
	v_mfma_f32_16x16x32_bf16 v[122:125], v[70:73], v[224:227], v[122:125]
	v_mfma_f32_16x16x32_bf16 v[110:113], v[54:57], v[232:235], v[110:113]
	v_mfma_f32_16x16x32_bf16 v[106:109], v[70:73], v[232:235], v[106:109]
	v_mfma_f32_16x16x32_bf16 v[94:97], v[54:57], v[240:243], v[94:97]
	v_mfma_f32_16x16x32_bf16 v[90:93], v[70:73], v[240:243], v[90:93]
	s_setprio 0
	s_setprio 1
	v_mfma_f32_16x16x32_bf16 v[134:137], v[164:167], v[212:215], v[134:137]
	v_mfma_f32_16x16x32_bf16 v[130:133], v[178:181], v[212:215], v[130:133]
	v_mfma_f32_16x16x32_bf16 v[118:121], v[164:167], v[220:223], v[118:121]
	v_mfma_f32_16x16x32_bf16 v[114:117], v[178:181], v[220:223], v[114:117]
	v_mfma_f32_16x16x32_bf16 v[102:105], v[164:167], v[228:231], v[102:105]
	v_mfma_f32_16x16x32_bf16 v[98:101], v[178:181], v[228:231], v[98:101]
	v_mfma_f32_16x16x32_bf16 v[86:89], v[164:167], v[236:239], v[86:89]
	v_mfma_f32_16x16x32_bf16 v[82:85], v[178:181], v[236:239], v[82:85]
	v_mfma_f32_16x16x32_bf16 v[134:137], v[168:171], v[216:219], v[134:137]
	v_mfma_f32_16x16x32_bf16 v[130:133], v[182:185], v[216:219], v[130:133]
	v_mfma_f32_16x16x32_bf16 v[118:121], v[168:171], v[224:227], v[118:121]
	v_mfma_f32_16x16x32_bf16 v[114:117], v[182:185], v[224:227], v[114:117]
	v_mfma_f32_16x16x32_bf16 v[102:105], v[168:171], v[232:235], v[102:105]
	v_mfma_f32_16x16x32_bf16 v[98:101], v[182:185], v[232:235], v[98:101]
	v_mfma_f32_16x16x32_bf16 v[86:89], v[168:171], v[240:243], v[86:89]
	v_mfma_f32_16x16x32_bf16 v[82:85], v[182:185], v[240:243], v[82:85]
	s_setprio 0
	s_barrier
	s_add_i32 s38, s42, s61
	v_lshl_add_u64 v[172:173], v[172:173], 0, s[20:21]
	s_mov_b32 m0, s38
	ds_read_b128 v[212:215], v177 offset:49152
	ds_read_b128 v[216:219], v177 offset:50176
	ds_read_b128 v[220:223], v177 offset:51200
	ds_read_b128 v[224:227], v177 offset:52224
	ds_read_b128 v[228:231], v177 offset:53248
	ds_read_b128 v[232:235], v177 offset:54272
	ds_read_b128 v[236:239], v177 offset:55296
	ds_read_b128 v[240:243], v177 offset:56320
	global_load_lds_dwordx4 v[172:173], off
	v_lshl_add_u64 v[172:173], v[186:187], 0, s[20:21]
	s_add_i32 m0, s38, 0x2000
	s_add_i32 s38, s43, s61
	global_load_lds_dwordx4 v[172:173], off
	v_lshl_add_u64 v[172:173], v[198:199], 0, s[20:21]
	s_mov_b32 m0, s38
	s_nop 0
	global_load_lds_dwordx4 v[172:173], off
	v_lshl_add_u64 v[172:173], v[244:245], 0, s[20:21]
	s_add_i32 m0, s38, 0x2000
	s_nop 0
	global_load_lds_dwordx4 v[172:173], off
	v_lshl_add_u64 v[172:173], v[246:247], 0, s[20:21]
	s_mov_b32 m0, s92
	s_nop 0
	global_load_lds_dwordx4 v[172:173], off
	v_lshl_add_u64 v[172:173], v[248:249], 0, s[20:21]
	s_mov_b32 m0, s93
	s_nop 0
	global_load_lds_dwordx4 v[172:173], off
	s_waitcnt vmcnt(8)
	s_waitcnt lgkmcnt(0)
	s_barrier
	s_setprio 1
	v_mfma_f32_16x16x32_bf16 v[78:81], v[50:53], v[212:215], v[78:81]
	v_mfma_f32_16x16x32_bf16 v[74:77], v[66:69], v[212:215], v[74:77]
	v_mfma_f32_16x16x32_bf16 v[62:65], v[50:53], v[220:223], v[62:65]
	v_mfma_f32_16x16x32_bf16 v[58:61], v[66:69], v[220:223], v[58:61]
	v_mfma_f32_16x16x32_bf16 v[30:33], v[50:53], v[228:231], v[30:33]
	v_mfma_f32_16x16x32_bf16 v[26:29], v[66:69], v[228:231], v[26:29]
	v_mfma_f32_16x16x32_bf16 v[14:17], v[50:53], v[236:239], v[14:17]
	v_mfma_f32_16x16x32_bf16 v[10:13], v[66:69], v[236:239], v[10:13]
	v_mfma_f32_16x16x32_bf16 v[78:81], v[54:57], v[216:219], v[78:81]
	v_mfma_f32_16x16x32_bf16 v[74:77], v[70:73], v[216:219], v[74:77]
	v_mfma_f32_16x16x32_bf16 v[62:65], v[54:57], v[224:227], v[62:65]
	v_mfma_f32_16x16x32_bf16 v[58:61], v[70:73], v[224:227], v[58:61]
	v_mfma_f32_16x16x32_bf16 v[30:33], v[54:57], v[232:235], v[30:33]
	v_mfma_f32_16x16x32_bf16 v[26:29], v[70:73], v[232:235], v[26:29]
	v_mfma_f32_16x16x32_bf16 v[14:17], v[54:57], v[240:243], v[14:17]
	v_mfma_f32_16x16x32_bf16 v[10:13], v[70:73], v[240:243], v[10:13]
	s_setprio 0
	s_setprio 1
	v_mfma_f32_16x16x32_bf16 v[38:41], v[164:167], v[212:215], v[38:41]
	v_mfma_f32_16x16x32_bf16 v[70:73], v[168:171], v[216:219], v[38:41]
	v_mfma_f32_16x16x32_bf16 v[38:41], v[178:181], v[212:215], v[46:49]
	v_mfma_f32_16x16x32_bf16 v[66:69], v[182:185], v[216:219], v[38:41]
	v_mfma_f32_16x16x32_bf16 v[38:41], v[164:167], v[220:223], v[42:45]
	v_mfma_f32_16x16x32_bf16 v[34:37], v[178:181], v[220:223], v[34:37]
	v_mfma_f32_16x16x32_bf16 v[22:25], v[164:167], v[228:231], v[22:25]
	v_mfma_f32_16x16x32_bf16 v[18:21], v[178:181], v[228:231], v[18:21]
	v_mfma_f32_16x16x32_bf16 v[6:9], v[164:167], v[236:239], v[6:9]
	v_mfma_f32_16x16x32_bf16 v[2:5], v[178:181], v[236:239], v[2:5]
	v_mfma_f32_16x16x32_bf16 v[42:45], v[168:171], v[224:227], v[38:41]
	v_mfma_f32_16x16x32_bf16 v[34:37], v[182:185], v[224:227], v[34:37]
	v_mfma_f32_16x16x32_bf16 v[22:25], v[168:171], v[232:235], v[22:25]
	v_mfma_f32_16x16x32_bf16 v[18:21], v[182:185], v[232:235], v[18:21]
	v_mfma_f32_16x16x32_bf16 v[6:9], v[168:171], v[240:243], v[6:9]
	v_mfma_f32_16x16x32_bf16 v[2:5], v[182:185], v[240:243], v[2:5]
	s_setprio 0
	s_barrier
	s_add_u32 s12, s12, 0x100
	s_addc_u32 s13, s13, 0
	s_add_u32 s40, s40, 0x100
	s_addc_u32 s41, s41, 0
	s_cmp_ge_u32 s58, s30
	s_mov_b32 s38, s58
	s_cbranch_scc0 .LBB0_682
	v_readlane_b32 s12, v254, 49
	v_readlane_b32 s13, v254, 50
	s_and_b64 vcc, exec, s[12:13]
	s_cbranch_vccz .LBB0_685
	s_barrier

.LBB0_812:
	s_add_u32 s38, s36, 0xfffc0080
	s_addc_u32 s39, s37, -1
	s_add_i32 s55, 0, 0x10000
	s_cmp_eq_u32 s54, 12
	s_cselect_b32 s41, s17, s39
	s_cselect_b32 s40, s50, s38
	v_add_u32_e32 v149, s55, v145
	s_cselect_b32 s39, s15, s53
	s_cselect_b32 s38, s51, s52
	s_add_i32 s58, 0, 0x14000
	ds_read_b128 v[140:143], v149
	ds_read_b128 v[150:153], v149 offset:1024
	ds_read_b128 v[164:167], v149 offset:2048
	ds_read_b128 v[168:171], v149 offset:3072
	v_add_u32_e32 v149, s58, v145
	ds_read_b128 v[176:179], v149
	ds_read_b128 v[180:183], v149 offset:1024
	ds_read_b128 v[184:187], v149 offset:2048
	ds_read_b128 v[212:215], v149 offset:3072
	v_lshl_add_u64 v[154:155], s[36:37], 0, v[136:137]
	s_add_i32 m0, s42, 0xc000
	ds_read_b128 v[216:219], v148
	ds_read_b128 v[220:223], v148 offset:1024
	ds_read_b128 v[224:227], v148 offset:2048
	ds_read_b128 v[228:231], v148 offset:3072
	ds_read_b128 v[232:235], v148 offset:4096
	ds_read_b128 v[236:239], v148 offset:5120
	ds_read_b128 v[240:243], v148 offset:6144
	ds_read_b128 v[244:247], v148 offset:7168
	global_load_lds_dwordx4 v[154:155], off
	v_lshl_add_u64 v[154:155], s[36:37], 0, v[138:139]
	s_add_i32 m0, s42, 0xe000
	s_nop 0
	global_load_lds_dwordx4 v[154:155], off
	s_waitcnt vmcnt(8)
	s_waitcnt lgkmcnt(0)
	s_barrier
	s_setprio 1
	v_mfma_f32_16x16x32_bf16 v[126:129], v[140:143], v[216:219], v[126:129]
	v_mfma_f32_16x16x32_bf16 v[118:121], v[164:167], v[216:219], v[118:121]
	v_mfma_f32_16x16x32_bf16 v[110:113], v[140:143], v[224:227], v[110:113]
	v_mfma_f32_16x16x32_bf16 v[102:105], v[164:167], v[224:227], v[102:105]
	v_mfma_f32_16x16x32_bf16 v[94:97], v[140:143], v[232:235], v[94:97]
	v_mfma_f32_16x16x32_bf16 v[86:89], v[164:167], v[232:235], v[86:89]
	v_mfma_f32_16x16x32_bf16 v[78:81], v[140:143], v[240:243], v[78:81]
	v_mfma_f32_16x16x32_bf16 v[70:73], v[164:167], v[240:243], v[70:73]
	v_mfma_f32_16x16x32_bf16 v[126:129], v[150:153], v[220:223], v[126:129]
	v_mfma_f32_16x16x32_bf16 v[118:121], v[168:171], v[220:223], v[118:121]
	v_mfma_f32_16x16x32_bf16 v[110:113], v[150:153], v[228:231], v[110:113]
	v_mfma_f32_16x16x32_bf16 v[102:105], v[168:171], v[228:231], v[102:105]
	v_mfma_f32_16x16x32_bf16 v[94:97], v[150:153], v[236:239], v[94:97]
	v_mfma_f32_16x16x32_bf16 v[86:89], v[168:171], v[236:239], v[86:89]
	v_mfma_f32_16x16x32_bf16 v[78:81], v[150:153], v[244:247], v[78:81]
	v_mfma_f32_16x16x32_bf16 v[70:73], v[168:171], v[244:247], v[70:73]
	s_setprio 0
	s_setprio 1
	v_mfma_f32_16x16x32_bf16 v[122:125], v[176:179], v[216:219], v[122:125]
	v_mfma_f32_16x16x32_bf16 v[114:117], v[184:187], v[216:219], v[114:117]
	v_mfma_f32_16x16x32_bf16 v[106:109], v[176:179], v[224:227], v[106:109]
	v_mfma_f32_16x16x32_bf16 v[98:101], v[184:187], v[224:227], v[98:101]
	v_mfma_f32_16x16x32_bf16 v[90:93], v[176:179], v[232:235], v[90:93]
	v_mfma_f32_16x16x32_bf16 v[82:85], v[184:187], v[232:235], v[82:85]
	v_mfma_f32_16x16x32_bf16 v[74:77], v[176:179], v[240:243], v[74:77]
	v_mfma_f32_16x16x32_bf16 v[66:69], v[184:187], v[240:243], v[66:69]
	v_mfma_f32_16x16x32_bf16 v[122:125], v[180:183], v[220:223], v[122:125]
	v_mfma_f32_16x16x32_bf16 v[114:117], v[212:215], v[220:223], v[114:117]
	v_mfma_f32_16x16x32_bf16 v[106:109], v[180:183], v[228:231], v[106:109]
	v_mfma_f32_16x16x32_bf16 v[98:101], v[212:215], v[228:231], v[98:101]
	v_mfma_f32_16x16x32_bf16 v[90:93], v[180:183], v[236:239], v[90:93]
	v_mfma_f32_16x16x32_bf16 v[82:85], v[212:215], v[236:239], v[82:85]
	v_mfma_f32_16x16x32_bf16 v[74:77], v[180:183], v[244:247], v[74:77]
	v_mfma_f32_16x16x32_bf16 v[66:69], v[212:215], v[244:247], v[66:69]
	s_setprio 0
	s_barrier
	s_add_i32 s55, s55, s7
	v_lshl_add_u64 v[154:155], s[38:39], 0, v[0:1]
	s_mov_b32 m0, s55
	ds_read_b128 v[216:219], v148 offset:16384
	ds_read_b128 v[220:223], v148 offset:17408
	ds_read_b128 v[224:227], v148 offset:18432
	ds_read_b128 v[228:231], v148 offset:19456
	ds_read_b128 v[232:235], v148 offset:20480
	ds_read_b128 v[236:239], v148 offset:21504
	ds_read_b128 v[240:243], v148 offset:22528
	ds_read_b128 v[244:247], v148 offset:23552
	global_load_lds_dwordx4 v[154:155], off
	s_add_i32 m0, s55, 0x2000
	s_add_u32 s56, s38, 0x40000
	v_lshl_add_u64 v[172:173], s[38:39], 0, v[134:135]
	s_addc_u32 s57, s39, 0
	s_add_i32 s55, s58, s7
	global_load_lds_dwordx4 v[172:173], off
	v_lshl_add_u64 v[248:249], s[56:57], 0, v[0:1]
	s_mov_b32 m0, s55
	v_lshl_add_u64 v[250:251], s[40:41], 0, v[132:133]
	global_load_lds_dwordx4 v[248:249], off
	v_lshl_add_u64 v[248:249], s[56:57], 0, v[134:135]
	s_add_i32 m0, s55, 0x2000
	s_nop 0
	global_load_lds_dwordx4 v[248:249], off
	v_lshl_add_u64 v[248:249], s[40:41], 0, v[130:131]
	s_mov_b32 m0, s42
	s_nop 0
	global_load_lds_dwordx4 v[248:249], off
	s_mov_b32 m0, s43
	s_nop 0
	global_load_lds_dwordx4 v[250:251], off
	s_waitcnt vmcnt(8)
	s_waitcnt lgkmcnt(0)
	s_barrier
	s_setprio 1
	v_mfma_f32_16x16x32_bf16 v[62:65], v[140:143], v[216:219], v[62:65]
	v_mfma_f32_16x16x32_bf16 v[54:57], v[164:167], v[216:219], v[54:57]
	v_mfma_f32_16x16x32_bf16 v[46:49], v[140:143], v[224:227], v[46:49]
	v_mfma_f32_16x16x32_bf16 v[38:41], v[164:167], v[224:227], v[38:41]
	v_mfma_f32_16x16x32_bf16 v[30:33], v[140:143], v[232:235], v[30:33]
	v_mfma_f32_16x16x32_bf16 v[22:25], v[164:167], v[232:235], v[22:25]
	v_mfma_f32_16x16x32_bf16 v[14:17], v[140:143], v[240:243], v[14:17]
	v_mfma_f32_16x16x32_bf16 v[6:9], v[164:167], v[240:243], v[6:9]
	v_mfma_f32_16x16x32_bf16 v[62:65], v[150:153], v[220:223], v[62:65]
	v_mfma_f32_16x16x32_bf16 v[54:57], v[168:171], v[220:223], v[54:57]
	v_mfma_f32_16x16x32_bf16 v[46:49], v[150:153], v[228:231], v[46:49]
	v_mfma_f32_16x16x32_bf16 v[38:41], v[168:171], v[228:231], v[38:41]
	v_mfma_f32_16x16x32_bf16 v[30:33], v[150:153], v[236:239], v[30:33]
	v_mfma_f32_16x16x32_bf16 v[22:25], v[168:171], v[236:239], v[22:25]
	v_mfma_f32_16x16x32_bf16 v[14:17], v[150:153], v[244:247], v[14:17]
	v_mfma_f32_16x16x32_bf16 v[6:9], v[168:171], v[244:247], v[6:9]
	s_setprio 0
	s_setprio 1
	v_mfma_f32_16x16x32_bf16 v[58:61], v[176:179], v[216:219], v[58:61]
	v_mfma_f32_16x16x32_bf16 v[50:53], v[184:187], v[216:219], v[50:53]
	v_mfma_f32_16x16x32_bf16 v[42:45], v[176:179], v[224:227], v[42:45]
	v_mfma_f32_16x16x32_bf16 v[34:37], v[184:187], v[224:227], v[34:37]
	v_mfma_f32_16x16x32_bf16 v[26:29], v[176:179], v[232:235], v[26:29]
	v_mfma_f32_16x16x32_bf16 v[18:21], v[184:187], v[232:235], v[18:21]
	v_mfma_f32_16x16x32_bf16 v[10:13], v[176:179], v[240:243], v[10:13]
	v_mfma_f32_16x16x32_bf16 v[2:5], v[184:187], v[240:243], v[2:5]
	v_mfma_f32_16x16x32_bf16 v[58:61], v[180:183], v[220:223], v[58:61]
	v_mfma_f32_16x16x32_bf16 v[50:53], v[212:215], v[220:223], v[50:53]
	v_mfma_f32_16x16x32_bf16 v[42:45], v[180:183], v[228:231], v[42:45]
	v_mfma_f32_16x16x32_bf16 v[34:37], v[212:215], v[228:231], v[34:37]
	v_mfma_f32_16x16x32_bf16 v[26:29], v[180:183], v[236:239], v[26:29]
	v_mfma_f32_16x16x32_bf16 v[18:21], v[212:215], v[236:239], v[18:21]
	v_mfma_f32_16x16x32_bf16 v[10:13], v[180:183], v[244:247], v[10:13]
	v_mfma_f32_16x16x32_bf16 v[2:5], v[212:215], v[244:247], v[2:5]
	s_setprio 0
	s_barrier
	s_add_i32 s55, 0, 0x18000
	v_add_u32_e32 v149, s55, v145
	s_add_i32 s56, 0, 0x1c000
	ds_read_b128 v[140:143], v149
	ds_read_b128 v[150:153], v149 offset:1024
	ds_read_b128 v[164:167], v149 offset:2048
	ds_read_b128 v[168:171], v149 offset:3072
	v_add_u32_e32 v149, s56, v145
	ds_read_b128 v[176:179], v149
	ds_read_b128 v[180:183], v149 offset:1024
	ds_read_b128 v[184:187], v149 offset:2048
	ds_read_b128 v[212:215], v149 offset:3072
	s_add_u32 s40, s40, 0x40000
	s_addc_u32 s41, s41, 0
	s_mov_b32 m0, s44
	v_lshl_add_u64 v[198:199], s[40:41], 0, v[130:131]
	ds_read_b128 v[216:219], v148 offset:32768
	ds_read_b128 v[220:223], v148 offset:33792
	ds_read_b128 v[224:227], v148 offset:34816
	ds_read_b128 v[228:231], v148 offset:35840
	ds_read_b128 v[232:235], v148 offset:36864
	ds_read_b128 v[236:239], v148 offset:37888
	ds_read_b128 v[240:243], v148 offset:38912
	ds_read_b128 v[244:247], v148 offset:39936
	global_load_lds_dwordx4 v[198:199], off
	v_lshl_add_u64 v[198:199], s[40:41], 0, v[132:133]
	s_mov_b32 m0, s45
	s_nop 0
	global_load_lds_dwordx4 v[198:199], off
	s_waitcnt vmcnt(8)
	s_waitcnt lgkmcnt(0)
	s_barrier
	s_setprio 1
	v_mfma_f32_16x16x32_bf16 v[126:129], v[140:143], v[216:219], v[126:129]
	v_mfma_f32_16x16x32_bf16 v[118:121], v[164:167], v[216:219], v[118:121]
	v_mfma_f32_16x16x32_bf16 v[110:113], v[140:143], v[224:227], v[110:113]
	v_mfma_f32_16x16x32_bf16 v[102:105], v[164:167], v[224:227], v[102:105]
	v_mfma_f32_16x16x32_bf16 v[94:97], v[140:143], v[232:235], v[94:97]
	v_mfma_f32_16x16x32_bf16 v[86:89], v[164:167], v[232:235], v[86:89]
	v_mfma_f32_16x16x32_bf16 v[78:81], v[140:143], v[240:243], v[78:81]
	v_mfma_f32_16x16x32_bf16 v[70:73], v[164:167], v[240:243], v[70:73]
	v_mfma_f32_16x16x32_bf16 v[126:129], v[150:153], v[220:223], v[126:129]
	v_mfma_f32_16x16x32_bf16 v[118:121], v[168:171], v[220:223], v[118:121]
	v_mfma_f32_16x16x32_bf16 v[110:113], v[150:153], v[228:231], v[110:113]
	v_mfma_f32_16x16x32_bf16 v[102:105], v[168:171], v[228:231], v[102:105]
	v_mfma_f32_16x16x32_bf16 v[94:97], v[150:153], v[236:239], v[94:97]
	v_mfma_f32_16x16x32_bf16 v[86:89], v[168:171], v[236:239], v[86:89]
	v_mfma_f32_16x16x32_bf16 v[78:81], v[150:153], v[244:247], v[78:81]
	v_mfma_f32_16x16x32_bf16 v[70:73], v[168:171], v[244:247], v[70:73]
	s_setprio 0
	s_setprio 1
	v_mfma_f32_16x16x32_bf16 v[122:125], v[176:179], v[216:219], v[122:125]
	v_mfma_f32_16x16x32_bf16 v[114:117], v[184:187], v[216:219], v[114:117]
	v_mfma_f32_16x16x32_bf16 v[106:109], v[176:179], v[224:227], v[106:109]
	v_mfma_f32_16x16x32_bf16 v[98:101], v[184:187], v[224:227], v[98:101]
	v_mfma_f32_16x16x32_bf16 v[90:93], v[176:179], v[232:235], v[90:93]
	v_mfma_f32_16x16x32_bf16 v[82:85], v[184:187], v[232:235], v[82:85]
	v_mfma_f32_16x16x32_bf16 v[74:77], v[176:179], v[240:243], v[74:77]
	v_mfma_f32_16x16x32_bf16 v[66:69], v[184:187], v[240:243], v[66:69]
	v_mfma_f32_16x16x32_bf16 v[122:125], v[180:183], v[220:223], v[122:125]
	v_mfma_f32_16x16x32_bf16 v[114:117], v[212:215], v[220:223], v[114:117]
	v_mfma_f32_16x16x32_bf16 v[106:109], v[180:183], v[228:231], v[106:109]
	v_mfma_f32_16x16x32_bf16 v[98:101], v[212:215], v[228:231], v[98:101]
	v_mfma_f32_16x16x32_bf16 v[90:93], v[180:183], v[236:239], v[90:93]
	v_mfma_f32_16x16x32_bf16 v[82:85], v[212:215], v[236:239], v[82:85]
	v_mfma_f32_16x16x32_bf16 v[74:77], v[180:183], v[244:247], v[74:77]
	v_mfma_f32_16x16x32_bf16 v[66:69], v[212:215], v[244:247], v[66:69]
	s_setprio 0
	s_barrier
	s_add_i32 s40, s55, s7
	v_lshl_add_u64 v[154:155], v[154:155], 0, s[20:21]
	s_mov_b32 m0, s40
	ds_read_b128 v[216:219], v148 offset:49152
	ds_read_b128 v[220:223], v148 offset:50176
	ds_read_b128 v[224:227], v148 offset:51200
	ds_read_b128 v[228:231], v148 offset:52224
	ds_read_b128 v[232:235], v148 offset:53248
	ds_read_b128 v[236:239], v148 offset:54272
	ds_read_b128 v[240:243], v148 offset:55296
	ds_read_b128 v[244:247], v148 offset:56320
	global_load_lds_dwordx4 v[154:155], off
	s_add_i32 m0, s40, 0x2000
	s_add_u32 s38, s38, 0x40080
	v_lshl_add_u64 v[154:155], v[172:173], 0, s[20:21]
	s_addc_u32 s39, s39, 0
	s_add_i32 s40, s56, s7
	global_load_lds_dwordx4 v[154:155], off
	v_lshl_add_u64 v[154:155], s[38:39], 0, v[0:1]
	s_mov_b32 m0, s40
	s_nop 0
	global_load_lds_dwordx4 v[154:155], off
	v_lshl_add_u64 v[154:155], s[38:39], 0, v[134:135]
	s_add_i32 m0, s40, 0x2000
	s_nop 0
	global_load_lds_dwordx4 v[154:155], off
	v_lshl_add_u64 v[154:155], v[248:249], 0, s[20:21]
	s_mov_b32 m0, s46
	s_nop 0
	global_load_lds_dwordx4 v[154:155], off
	v_lshl_add_u64 v[154:155], v[250:251], 0, s[20:21]
	s_mov_b32 m0, s47
	s_nop 0
	global_load_lds_dwordx4 v[154:155], off
	s_waitcnt vmcnt(8)
	s_waitcnt lgkmcnt(0)
	s_barrier
	s_setprio 1
	v_mfma_f32_16x16x32_bf16 v[62:65], v[140:143], v[216:219], v[62:65]
	v_mfma_f32_16x16x32_bf16 v[54:57], v[164:167], v[216:219], v[54:57]
	v_mfma_f32_16x16x32_bf16 v[46:49], v[140:143], v[224:227], v[46:49]
	v_mfma_f32_16x16x32_bf16 v[38:41], v[164:167], v[224:227], v[38:41]
	v_mfma_f32_16x16x32_bf16 v[30:33], v[140:143], v[232:235], v[30:33]
	v_mfma_f32_16x16x32_bf16 v[22:25], v[164:167], v[232:235], v[22:25]
	v_mfma_f32_16x16x32_bf16 v[14:17], v[140:143], v[240:243], v[14:17]
	v_mfma_f32_16x16x32_bf16 v[6:9], v[164:167], v[240:243], v[6:9]
	v_mfma_f32_16x16x32_bf16 v[62:65], v[150:153], v[220:223], v[62:65]
	v_mfma_f32_16x16x32_bf16 v[54:57], v[168:171], v[220:223], v[54:57]
	v_mfma_f32_16x16x32_bf16 v[46:49], v[150:153], v[228:231], v[46:49]
	v_mfma_f32_16x16x32_bf16 v[38:41], v[168:171], v[228:231], v[38:41]
	v_mfma_f32_16x16x32_bf16 v[30:33], v[150:153], v[236:239], v[30:33]
	v_mfma_f32_16x16x32_bf16 v[22:25], v[168:171], v[236:239], v[22:25]
	v_mfma_f32_16x16x32_bf16 v[14:17], v[150:153], v[244:247], v[14:17]
	v_mfma_f32_16x16x32_bf16 v[6:9], v[168:171], v[244:247], v[6:9]
	s_setprio 0
	s_setprio 1
	v_mfma_f32_16x16x32_bf16 v[58:61], v[176:179], v[216:219], v[58:61]
	v_mfma_f32_16x16x32_bf16 v[50:53], v[184:187], v[216:219], v[50:53]
	v_mfma_f32_16x16x32_bf16 v[42:45], v[176:179], v[224:227], v[42:45]
	v_mfma_f32_16x16x32_bf16 v[34:37], v[184:187], v[224:227], v[34:37]
	v_mfma_f32_16x16x32_bf16 v[26:29], v[176:179], v[232:235], v[26:29]
	v_mfma_f32_16x16x32_bf16 v[18:21], v[184:187], v[232:235], v[18:21]
	v_mfma_f32_16x16x32_bf16 v[10:13], v[176:179], v[240:243], v[10:13]
	v_mfma_f32_16x16x32_bf16 v[2:5], v[184:187], v[240:243], v[2:5]
	v_mfma_f32_16x16x32_bf16 v[58:61], v[180:183], v[220:223], v[58:61]
	v_mfma_f32_16x16x32_bf16 v[50:53], v[212:215], v[220:223], v[50:53]
	v_mfma_f32_16x16x32_bf16 v[42:45], v[180:183], v[228:231], v[42:45]
	v_mfma_f32_16x16x32_bf16 v[34:37], v[212:215], v[228:231], v[34:37]
	v_mfma_f32_16x16x32_bf16 v[26:29], v[180:183], v[236:239], v[26:29]
	v_mfma_f32_16x16x32_bf16 v[18:21], v[212:215], v[236:239], v[18:21]
	v_mfma_f32_16x16x32_bf16 v[10:13], v[180:183], v[244:247], v[10:13]
	v_mfma_f32_16x16x32_bf16 v[2:5], v[212:215], v[244:247], v[2:5]
	s_setprio 0
	s_barrier
	s_add_i32 s54, s54, 2
	s_add_u32 s36, s36, 0x100
	s_addc_u32 s37, s37, 0
	s_add_u32 s52, s52, 0x100
	s_addc_u32 s53, s53, 0
	s_cmp_gt_u32 s54, 13
	s_cbranch_scc0 .LBB0_812
	s_and_b64 vcc, exec, s[12:13]
	s_cbranch_vccz .LBB0_815
	s_barrier
